# gdn_prep: a_log/dt_bias read once into SGPRs, exact loop-top vmcnt (no full drain inside the unit loop); on top of hoisted LDS reads in solve/k_tail/substitution/output stages
# baseline (speedup 1.0000x reference)
; DI float sigmf(float v) { return __builtin_amdgcn_rcpf(1.0f + __expf(-v)); }
; DI float softplusf(float v) { return v > 20.f ? v : __logf(1.0f + __expf(v)); }
; DI void gdn_prep_unit(const Params& P, int h, int n, unsigned char* lds, int tid, u32x4 (&raw)[12], float& sbv, float& sav, int unext, bool cw_lds = false) {
;     unsigned char* ws = P.ws;
;     bf16_t* Kimg = (bf16_t*)(lds); bf16_t* Qimg = (bf16_t*)(lds + 9216);
;     float* Ml = (float*)(lds + 18432); float* X = (float*)(lds + 35840);
;     float* graw = (float*)(lds + 69632); float* gcs = graw + 64; float* bet = graw + 128;
;     bf16_t* Aimg = (bf16_t*)(lds + 76800);
;     const bf16_t* PROJ = (const bf16_t*)(ws + WS_PROJ); const float* SM = (const float*)(ws + WS_SMALL);
;     const float* convw = P.in[4];
;     const int unit = h * 256 + n;
;     bf16_t* IMG = (bf16_t*)P.out + (size_t)unit * 16384;
;     const int lane = tid & 63, wave = tid >> 6;
;     const int t = tid >> 3, c8 = tid & 7, tok = n * 64 + t;
;     ...
;     const float rq = rsqrtf(ssq + EPS) * 0.125f, rk = rsqrtf(ssk + EPS);
;     const float beta = sigmf(sb_c);
;     const float gt = -__expf(P.in[5][h]) * softplusf(sa_c + P.in[6][h]);
.LBB0_490:
	s_or_b64 exec, exec, s[4:5]
	v_mov_b32_e32 v42, 0
	v_mov_b32_e32 v53, v42
	v_and_b32_e32 v122, 7, v162
	v_lshl_add_u64 v[84:85], s[66:67], 0, v[52:53]
	v_mul_u32_u24_e32 v52, 0x48, v196
	s_lshl_b32 s72, s61, 8
	v_lshlrev_b32_e32 v57, 4, v122
	v_lshlrev_b32_e32 v52, 1, v52
	s_add_u32 s80, s74, s0
	v_add3_u32 v137, 0, v57, v52
	v_and_b32_e32 v60, 32, v130
	v_lshlrev_b32_e32 v52, 4, v162
	s_addc_u32 s81, s75, 0
	v_and_or_b32 v57, v52, 16, v60
	s_add_u32 s86, s76, s0
	v_lshrrev_b32_e32 v62, 4, v162
	v_bfe_u32 v58, v162, 4, 3
	v_lshrrev_b32_e32 v57, 3, v57
	s_addc_u32 s87, s77, 0
	global_load_dword v236, v42, s[80:81]
	global_load_dword v237, v42, s[86:87]
	v_lshlrev_b32_e32 v56, 2, v196
	s_add_i32 s33, 0, 0x11000
	s_add_i32 s0, 0, 0x11200
	s_add_i32 s1, 0, 0x11100
	v_bitop3_b32 v63, v57, v62, 7 bitop3:0x78
	v_bitop3_b32 v64, v57, v58, 1 bitop3:0x36
	v_lshrrev_b32_e32 v124, 4, v163
	v_lshrrev_b32_e32 v57, 7, v162
	v_add_u32_e32 v132, s33, v56
	v_add_u32_e32 v133, s0, v56
	v_add_u32_e32 v136, s1, v56
	v_lshlrev_b32_e32 v56, 1, v162
	v_and_b32_e32 v127, 15, v162
	v_and_b32_e32 v58, 2, v131
	v_lshlrev_b32_e32 v59, 4, v57
	v_lshlrev_b32_e32 v128, 2, v124
	v_or_b32_e32 v66, v59, v127
	v_and_b32_e32 v126, 24, v56
	v_or_b32_e32 v56, v128, v59
	v_lshlrev_b32_e32 v59, 4, v58
	v_or_b32_e32 v67, v59, v127
	v_and_b32_e32 v61, 48, v163
	v_lshlrev_b32_e32 v69, 2, v67
	s_movk_i32 s2, 0x210
	v_add_u32_e32 v65, 0, v61
	v_mul_u32_u24_e32 v66, 0x48, v66
	v_add_u32_e32 v140, s1, v69
	v_add_u32_e32 v141, 0, v69
	v_lshlrev_b32_e32 v69, 2, v56
	v_and_b32_e32 v125, 48, v162
	v_mad_u32_u24 v53, v196, s2, 0
	v_lshl_add_u32 v139, v66, 1, v65
	v_and_b32_e32 v66, 3, v162
	v_or_b32_e32 v70, v59, v126
	v_add_u32_e32 v142, s1, v69
	v_bitop3_b32 v59, v59, v125, v126 bitop3:0x36
	s_add_i32 s2, 0, 0x12c00
	v_add_u32_e32 v144, s0, v69
	v_or_b32_e32 v69, 1, v56
	v_lshl_add_u32 v71, v56, 7, s2
	v_lshlrev_b32_e32 v59, 1, v59
	v_lshlrev_b32_e32 v72, 1, v66
	v_lshl_add_u32 v73, v69, 7, s2
	v_add3_u32 v143, v71, v59, v72
	v_lshlrev_b32_e32 v71, 2, v69
	v_add3_u32 v147, v73, v59, v72
	v_or_b32_e32 v59, 2, v56
	v_add_u32_e32 v146, s1, v71
	v_add_u32_e32 v148, s0, v71
	v_lshlrev_b32_e32 v71, 2, v59
	v_bitop3_b32 v73, v71, v70, 56 bitop3:0x6c
	v_add_u32_e32 v149, s1, v71
	v_lshl_add_u32 v74, v59, 7, s2
	v_lshlrev_b32_e32 v73, 1, v73
	v_add_u32_e32 v151, s0, v71
	v_or_b32_e32 v71, 3, v56
	v_add3_u32 v150, v74, v73, v72
	v_lshlrev_b32_e32 v73, 2, v71
	v_bitop3_b32 v70, v73, v70, 56 bitop3:0x6c
	v_mul_u32_u24_e32 v68, 0x90, v67
	v_cmp_le_u32_e64 s[12:13], v67, v56
	v_cmp_lt_u32_e64 s[14:15], v67, v56
	v_cmp_le_u32_e64 s[16:17], v67, v69
	v_cmp_le_u32_e64 s[18:19], v67, v59
	v_cmp_lt_u32_e64 s[20:21], v67, v59
	v_cmp_le_u32_e64 s[22:23], v67, v71
	v_lshl_add_u32 v74, v71, 7, s2
	v_lshlrev_b32_e32 v70, 1, v70
	v_cmp_lt_u32_e64 s[24:25], v67, v71
	v_add_u32_e32 v154, s0, v73
	v_or_b32_e32 v67, 16, v67
	s_movk_i32 s0, 0x100
	v_add3_u32 v153, v74, v70, v72
	v_mul_u32_u24_e32 v70, 0x90, v67
	v_lshl_add_u32 v155, v67, 2, s1
	v_cmp_le_u32_e64 s[28:29], v67, v56
	v_cmp_lt_u32_e64 s[30:31], v67, v56
	v_cmp_le_u32_e64 s[34:35], v67, v69
	v_cmp_le_u32_e64 s[36:37], v67, v59
	v_cmp_lt_u32_e64 s[38:39], v67, v59
	v_cmp_le_u32_e64 s[40:41], v67, v71
	v_cmp_lt_u32_e64 s[42:43], v67, v71
	v_subrev_co_u32_e32 v67, vcc, s0, v162
	s_xor_b64 s[88:89], vcc, -1
	v_lshrrev_b32_e32 v72, 2, v163
	v_cmp_gt_u32_e32 vcc, 4, v163
	v_cmp_eq_u32_e64 s[44:45], s0, v162
	v_and_b32_e32 v74, 60, v163
	v_cndmask_b32_e64 v170, 0, 1.0, vcc
	v_cmp_eq_u32_e32 vcc, 1, v72
	s_add_i32 s0, 0, 0x11300
	v_add_u32_e32 v74, s0, v74
	v_cndmask_b32_e64 v171, 0, 1.0, vcc
	v_cmp_eq_u32_e32 vcc, 2, v72
	v_add_u32_e32 v78, s0, v61
	s_and_b32 s0, s63, 0xffffffc0
	v_cndmask_b32_e64 v175, 0, 1.0, vcc
	v_cmp_eq_u32_e32 vcc, 3, v72
	s_movk_i32 s3, 0x110
	v_add_u32_e32 v152, s1, v73
	v_cndmask_b32_e64 v176, 0, 1.0, vcc
	v_cmp_eq_u32_e32 vcc, 4, v72
	v_and_b32_e32 v55, 12, v55
	v_lshl_add_u32 v73, v1, 6, 0
	v_cndmask_b32_e64 v179, 0, 1.0, vcc
	v_cmp_eq_u32_e32 vcc, 5, v72
	v_lshl_or_b32 v75, v1, 4, 1
	v_or_b32_e32 v61, 16, v127
	v_cndmask_b32_e64 v180, 0, 1.0, vcc
	v_cmp_eq_u32_e32 vcc, 6, v72
	s_or_b32 s0, s0, s61
	v_mul_u32_u24_e32 v145, 0x110, v56
	v_cndmask_b32_e64 v183, 0, 1.0, vcc
	v_cmp_eq_u32_e32 vcc, 7, v72
	v_or_b32_e32 v56, v55, v60
	v_mad_u32_u24 v161, v75, s3, v73
	v_cndmask_b32_e64 v185, 0, 1.0, vcc
	v_cmp_eq_u32_e32 vcc, 8, v72
	v_mad_u32_u24 v207, v61, s3, v65
	s_or_b32 s3, s0, 8
	v_cndmask_b32_e64 v189, 0, 1.0, vcc
	v_cmp_eq_u32_e32 vcc, 9, v72
	s_add_i32 s0, s72, s54
	v_add_u32_e32 v135, s1, v166
	v_cndmask_b32_e64 v190, 0, 1.0, vcc
	v_cmp_eq_u32_e32 vcc, 10, v72
	v_lshl_add_u32 v157, v56, 2, s1
	s_ashr_i32 s1, s0, 31
	v_cndmask_b32_e64 v194, 0, 1.0, vcc
	v_cmp_eq_u32_e32 vcc, 11, v72
	v_readlane_b32 s56, v239, 1
; DI float sigmf(float v) { return __builtin_amdgcn_rcpf(1.0f + __expf(-v)); }
; DI float softplusf(float v) { return v > 20.f ? v : __logf(1.0f + __expf(v)); }
; DI void gdn_prep_unit(const Params& P, int h, int n, unsigned char* lds, int tid, u32x4 (&raw)[12], float& sbv, float& sav, int unext, bool cw_lds = false) {
;     ...
;     const int unit = h * 256 + n;
;     bf16_t* IMG = (bf16_t*)P.out + (size_t)unit * 16384;
;     const int lane = tid & 63, wave = tid >> 6;
;     const int t = tid >> 3, c8 = tid & 7, tok = n * 64 + t;
;     ...
;     const float rq = rsqrtf(ssq + EPS) * 0.125f, rk = rsqrtf(ssk + EPS);
;     const float beta = sigmf(sb_c);
;     const float gt = -__expf(P.in[5][h]) * softplusf(sa_c + P.in[6][h]);
	v_lshrrev_b32_e32 v61, 2, v162
	v_cndmask_b32_e64 v195, 0, 1.0, vcc
	v_cmp_eq_u32_e32 vcc, 12, v72
	s_lshl_b64 s[4:5], s[0:1], 2
	v_readlane_b32 s58, v239, 3
	v_cndmask_b32_e64 v200, 0, 1.0, vcc
	v_cmp_eq_u32_e32 vcc, 13, v72
	v_lshl_add_u32 v159, v67, 4, s2
	v_lshl_add_u32 v160, v130, 1, s2
	v_cndmask_b32_e64 v201, 0, 1.0, vcc
	v_cmp_eq_u32_e32 vcc, 14, v72
	v_and_b32_e32 v81, 60, v61
	v_readlane_b32 s59, v239, 4
	s_add_u32 s2, s58, s4
	v_mul_u32_u24_e32 v76, 0x1100, v1
	v_lshlrev_b32_e32 v77, 2, v66
	v_add_u32_e32 v172, 0x220, v161
	v_add_u32_e32 v177, 0x440, v161
	v_add_u32_e32 v181, 0x660, v161
	v_add_u32_e32 v186, 0x880, v161
	v_add_u32_e32 v191, 0xaa0, v161
	v_add_u32_e32 v197, 0xcc0, v161
	v_add_u32_e32 v202, 0xee0, v161
	v_cndmask_b32_e64 v205, 0, 1.0, vcc
	v_cmp_eq_u32_e32 vcc, 15, v72
	v_and_b32_e32 v123, 0x3c0, v162
	v_lshlrev_b32_e32 v72, 2, v127
	v_mul_u32_u24_e32 v81, 0x210, v81
	s_addc_u32 s5, s59, s5
	v_add3_u32 v168, v73, v76, v77
	v_add_u32_e32 v169, v161, v77
	v_add_u32_e32 v173, v172, v77
	v_add_u32_e32 v178, v177, v77
	v_add_u32_e32 v182, v181, v77
	v_add_u32_e32 v187, v186, v77
	v_add_u32_e32 v192, v191, v77
	v_add_u32_e32 v198, v197, v77
	v_add_u32_e32 v203, v202, v77
	v_add3_u32 v77, 0, v123, v72
	v_add3_u32 v72, 0, v81, v72
	v_and_b32_e32 v61, 0xc0, v61
	s_add_u32 s4, s2, 0x10000
	v_add_u32_e32 v210, v72, v61
	v_add_u32_e32 v61, 0x200, v162
	s_addc_u32 s5, s5, 0
	s_lshl_b64 s[74:75], s[0:1], 13
	v_lshrrev_b32_e32 v61, 2, v61
	s_mov_b32 s64, s54
	s_add_u32 s54, s58, s74
	v_lshlrev_b32_e32 v129, 5, v122
	v_mov_b32_e32 v131, v42
	v_and_b32_e32 v61, 0x1c0, v61
	v_lshlrev_b32_e32 v55, 2, v55
	v_lshlrev_b32_e32 v60, 2, v60
	s_addc_u32 s55, s59, s75
	v_add_u32_e32 v138, v53, v129
	v_add_u32_e32 v211, v72, v61
	v_add3_u32 v212, v53, v55, v60
	v_lshl_add_u64 v[60:61], s[54:55], 0, v[130:131]
	s_mov_b64 s[54:55], 0x1500000
	s_lshl_b64 s[62:63], s[0:1], 15
	v_and_b32_e32 v53, 0x3f80, v52
	v_lshl_add_u64 v[86:87], v[60:61], 0, s[54:55]
	v_or_b32_e32 v60, s62, v53
	v_lshlrev_b32_e32 v53, 4, v63
	v_and_b32_e32 v63, 8, v54
	v_readlane_b32 s57, v239, 2
	v_or3_b32 v54, v60, v53, v63
	v_mov_b32_e32 v55, s63
	v_lshl_add_u64 v[54:55], s[56:57], 0, v[54:55]
	s_mov_b64 s[84:85], 0x2000
	v_mov_b32_e32 v61, s63
	v_lshl_add_u64 v[88:89], v[54:55], 0, s[84:85]
	v_lshlrev_b32_e32 v54, 4, v64
	v_mov_b32_e32 v55, v42
	v_lshl_add_u64 v[54:55], v[60:61], 0, v[54:55]
	v_or_b32_e32 v54, v54, v63
	v_bitop3_b32 v53, v62, 7, v162 bitop3:0x48
	v_cmp_le_u32_e64 s[10:11], v58, v57
	v_cmp_lt_u32_e64 s[26:27], v58, v57
	v_lshrrev_b32_e32 v57, 3, v67
	v_lshl_add_u64 v[54:55], s[56:57], 0, v[54:55]
	v_lshlrev_b32_e32 v53, 4, v53
	v_mul_u32_u24_e32 v69, 0x90, v56
	v_lshl_add_u32 v71, v57, 1, 0
	v_lshlrev_b32_e32 v56, 6, v57
	v_mov_b32_e32 v57, v42
	v_lshl_add_u64 v[90:91], v[54:55], 0, s[84:85]
	v_or_b32_e32 v54, s62, v53
	v_mov_b32_e32 v55, s63
	v_lshl_add_u64 v[54:55], v[56:57], 1, v[54:55]
	v_lshl_add_u64 v[54:55], s[56:57], 0, v[54:55]
	s_mov_b64 s[0:1], 0x6000
	v_lshl_add_u64 v[92:93], v[54:55], 0, s[0:1]
	s_add_u32 s0, s56, s62
	v_lshlrev_b32_e32 v58, 3, v67
	v_mov_b32_e32 v59, v42
	v_or_b32_e32 v60, v60, v53
	s_addc_u32 s1, s57, s63
	v_mov_b32_e32 v53, v42
	v_lshl_add_u32 v67, v196, 1, 0
	v_cmp_eq_u32_e64 s[46:47], 0, v66
	v_cmp_eq_u32_e64 s[48:49], 1, v66
	v_mul_u32_u24_e32 v73, 0x500, v1
	v_mul_u32_u24_e32 v75, 0x50, v75
	v_cmp_eq_u32_e64 s[50:51], 2, v66
	v_cmp_eq_u32_e64 s[52:53], 3, v66
	v_add_u32_e32 v66, 0x110, v173
	v_add_u32_e32 v76, 0x110, v178
	v_mul_u32_u24_e32 v79, 0x840, v124
	v_mul_u32_u24_e32 v80, 0x50, v127
	v_lshl_add_u64 v[54:55], v[58:59], 1, s[0:1]
	s_mov_b64 s[54:55], 0x4000
	v_lshl_add_u64 v[52:53], s[0:1], 0, v[52:53]
	v_cmp_gt_u32_e64 s[8:9], 64, v162
	v_add_u32_e32 v134, s33, v166
	v_add_u32_e32 v158, 64, v157
	v_add_u32_e32 v174, 0xfffffef0, v173
	v_add_u32_e32 v188, 0x110, v182
	v_add_u32_e32 v193, 0x110, v187
	v_add_u32_e32 v199, 0x110, v192
	v_add_u32_e32 v204, 0x110, v198
	v_cndmask_b32_e64 v206, 0, 1.0, vcc
	v_add_u32_e32 v208, 0x1100, v207
	v_add_u32_e32 v209, 0x2200, v207
	v_lshl_add_u64 v[94:95], s[56:57], 0, v[60:61]
	v_lshl_add_u64 v[96:97], v[54:55], 0, s[54:55]
	v_lshl_add_u64 v[98:99], v[52:53], 0, s[54:55]
	s_mov_b64 s[96:97], 0
	s_mov_b32 s58, 0x800000
	s_add_i32 s59, 0, 0x111fc
	v_add_u32_e32 v130, v71, v69
	v_add_u32_e32 v131, v67, v69
	v_add_u32_e32 v213, v74, v73
	v_add_u32_e32 v214, v74, v75
	v_add_u32_e32 v215, v77, v79
	v_add_u32_e32 v216, v78, v80
	v_mov_b32_e32 v217, 0x41b17218
	v_add_u32_e32 v218, v65, v68
	v_add_u32_e32 v219, v65, v70
	v_add_u32_e32 v220, 0x4800, v66
	v_add_u32_e32 v221, 0x4800, v76
	s_mov_b32 s68, 0
	s_mov_b32 s78, 0x80008000
	s_waitcnt lgkmcnt(0)
	s_barrier
	s_waitcnt vmcnt(0)
	v_readfirstlane_b32 s100, v236
	v_readfirstlane_b32 s101, v237
	s_branch .LBB0_492

; __device__ __forceinline__ float bflo(unsigned u) { return __uint_as_float(u << 16); }
; __device__ __forceinline__ float bfhi(unsigned u) { return __uint_as_float(u & 0xffff0000u); }
; DI float bflo(unsigned u) { return __uint_as_float(u << 16); }
; DI float bfhi(unsigned u) { return __uint_as_float(u & 0xffff0000u); }
; DI float sigmf(float v) { return __builtin_amdgcn_rcpf(1.0f + __expf(-v)); }
; DI void gdn_prep_unit(const Params& P, int h, int n, unsigned char* lds, int tid, u32x4 (&raw)[12], float& sbv, float& sav, int unext, bool cw_lds = false) {
;     ...
; #pragma unroll
;     for (int xx = 0; xx < 3; ++xx) {
;         float acc[8];
; #pragma unroll
;         for (int e = 0; e < 8; ++e) acc[e] = 0.f;
; #pragma unroll
;         for (int j = 0; j < 4; ++j) { const u32x4 rw = raw[xx * 4 + j];
;             const float* wp = cw_lds ? (const float*)(lds + 86016) + (j * 3 + xx) * 64 + 8 * c8 : convw + j * 1536 + xx * 512 + h * 64 + 8 * c8;
;             const f32x4 w0 = *(const f32x4*)wp, w1 = *(const f32x4*)(wp + 4);
;             acc[0] += w0.x * bflo(rw.x); acc[1] += w0.y * bfhi(rw.x); acc[2] += w0.z * bflo(rw.y); acc[3] += w0.w * bfhi(rw.y);
;             acc[4] += w1.x * bflo(rw.z); acc[5] += w1.y * bfhi(rw.z); acc[6] += w1.z * bflo(rw.w); acc[7] += w1.w * bfhi(rw.w); }
; #pragma unroll
;         for (int e = 0; e < 8; ++e) y[xx][e] = acc[e] * sigmf(acc[e]);
;     }
.LBB0_492:
	s_nop 0
	v_add_u32_e32 v52, 0, v129
	v_add_u32_e32 v116, 0x15000, v52
	ds_read_b128 v[52:55], v116
	ds_read_b128 v[56:59], v116 offset:16
	ds_read_b128 v[60:63], v116 offset:768
	ds_read_b128 v[64:67], v116 offset:784
	ds_read_b128 v[68:71], v116 offset:1536
	ds_read_b128 v[72:75], v116 offset:1552
	ds_read_b128 v[76:79], v116 offset:2304
	ds_read_b128 v[80:83], v116 offset:2320
	s_waitcnt vmcnt(3)
	v_lshlrev_b32_e32 v100, 16, v6
	v_and_b32_e32 v101, 0xffff0000, v6
	s_waitcnt lgkmcnt(7)
	v_pk_fma_f32 v[52:53], v[52:53], v[100:101], 0 op_sel_hi:[1,1,0]
	v_lshlrev_b32_e32 v100, 16, v2
	v_and_b32_e32 v101, 0xffff0000, v2
	s_waitcnt lgkmcnt(5)
	v_pk_fma_f32 v[52:53], v[60:61], v[100:101], v[52:53]
	v_lshlrev_b32_e32 v60, 16, v10
	v_and_b32_e32 v61, 0xffff0000, v10
	s_waitcnt lgkmcnt(3)
	v_pk_fma_f32 v[52:53], v[68:69], v[60:61], v[52:53]
	v_lshlrev_b32_e32 v60, 16, v14
	v_and_b32_e32 v61, 0xffff0000, v14
	s_waitcnt lgkmcnt(1)
	v_pk_fma_f32 v[52:53], v[76:77], v[60:61], v[52:53]
	v_lshlrev_b32_e32 v68, 16, v7
	v_mul_f32_e32 v60, 0xbfb8aa3b, v52
	v_mul_f32_e32 v61, 0xbfb8aa3b, v53
	v_and_b32_e32 v69, 0xffff0000, v7
	v_exp_f32_e32 v60, v60
	v_exp_f32_e32 v61, v61
	v_pk_fma_f32 v[54:55], v[54:55], v[68:69], 0 op_sel_hi:[1,1,0]
	v_lshlrev_b32_e32 v68, 16, v3
	v_and_b32_e32 v69, 0xffff0000, v3
	v_pk_fma_f32 v[54:55], v[62:63], v[68:69], v[54:55]
	v_lshlrev_b32_e32 v62, 16, v11
	v_and_b32_e32 v63, 0xffff0000, v11
	v_pk_fma_f32 v[54:55], v[70:71], v[62:63], v[54:55]
	v_lshlrev_b32_e32 v62, 16, v15
	v_and_b32_e32 v63, 0xffff0000, v15
	v_pk_fma_f32 v[54:55], v[78:79], v[62:63], v[54:55]
	v_add_f32_e32 v60, 1.0, v60
	v_add_f32_e32 v61, 1.0, v61
	v_mul_f32_e32 v62, 0xbfb8aa3b, v54
	v_mul_f32_e32 v63, 0xbfb8aa3b, v55
	v_rcp_f32_e32 v60, v60
	v_rcp_f32_e32 v61, v61
	v_exp_f32_e32 v62, v62
	v_exp_f32_e32 v63, v63
	v_lshlrev_b32_e32 v110, 16, v18
	v_pk_mul_f32 v[100:101], v[52:53], v[60:61]
	v_add_f32_e32 v52, 1.0, v62
	v_add_f32_e32 v53, 1.0, v63
	v_lshlrev_b32_e32 v60, 16, v8
	v_and_b32_e32 v61, 0xffff0000, v8
	v_rcp_f32_e32 v52, v52
	v_rcp_f32_e32 v53, v53
	v_pk_fma_f32 v[56:57], v[56:57], v[60:61], 0 op_sel_hi:[1,1,0]
	v_lshlrev_b32_e32 v60, 16, v4
	v_and_b32_e32 v61, 0xffff0000, v4
	v_pk_fma_f32 v[56:57], v[64:65], v[60:61], v[56:57]
	v_lshlrev_b32_e32 v60, 16, v12
	v_and_b32_e32 v61, 0xffff0000, v12
	v_pk_fma_f32 v[56:57], v[72:73], v[60:61], v[56:57]
	v_lshlrev_b32_e32 v60, 16, v16
	v_and_b32_e32 v61, 0xffff0000, v16
	s_waitcnt lgkmcnt(0)
	v_pk_fma_f32 v[56:57], v[80:81], v[60:61], v[56:57]
	v_pk_mul_f32 v[102:103], v[54:55], v[52:53]
	v_mul_f32_e32 v60, 0xbfb8aa3b, v56
	v_mul_f32_e32 v61, 0xbfb8aa3b, v57
	v_lshlrev_b32_e32 v54, 16, v9
	v_and_b32_e32 v55, 0xffff0000, v9
	v_exp_f32_e32 v60, v60
	v_exp_f32_e32 v61, v61
	v_pk_fma_f32 v[54:55], v[58:59], v[54:55], 0 op_sel_hi:[1,1,0]
	v_lshlrev_b32_e32 v58, 16, v5
	v_and_b32_e32 v59, 0xffff0000, v5
	v_pk_fma_f32 v[54:55], v[66:67], v[58:59], v[54:55]
	v_lshlrev_b32_e32 v58, 16, v13
	v_and_b32_e32 v59, 0xffff0000, v13
	v_pk_fma_f32 v[54:55], v[74:75], v[58:59], v[54:55]
	v_lshlrev_b32_e32 v58, 16, v17
	v_and_b32_e32 v59, 0xffff0000, v17
	v_pk_fma_f32 v[106:107], v[82:83], v[58:59], v[54:55]
	v_add_f32_e32 v52, 1.0, v60
	v_add_f32_e32 v53, 1.0, v61
	v_mul_f32_e32 v54, 0xbfb8aa3b, v106
	v_rcp_f32_e32 v52, v52
	v_rcp_f32_e32 v53, v53
	v_exp_f32_e32 v54, v54
	v_mul_f32_e32 v55, 0xbfb8aa3b, v107
	v_exp_f32_e32 v55, v55
	v_pk_mul_f32 v[104:105], v[56:57], v[52:53]
	v_add_f32_e32 v52, 1.0, v54
	v_rcp_f32_e32 v108, v52
	v_add_f32_e32 v52, 1.0, v55
	v_rcp_f32_e32 v109, v52
	ds_read_b128 v[52:55], v116 offset:256
	ds_read_b128 v[56:59], v116 offset:272
	ds_read_b128 v[60:63], v116 offset:1024
	ds_read_b128 v[64:67], v116 offset:1040
	ds_read_b128 v[68:71], v116 offset:1792
	ds_read_b128 v[72:75], v116 offset:1808
	ds_read_b128 v[76:79], v116 offset:2560
	ds_read_b128 v[80:83], v116 offset:2576
	v_and_b32_e32 v111, 0xffff0000, v18
	s_waitcnt lgkmcnt(7)
	v_pk_fma_f32 v[52:53], v[52:53], v[110:111], 0 op_sel_hi:[1,1,0]
	v_lshlrev_b32_e32 v110, 16, v22
	v_and_b32_e32 v111, 0xffff0000, v22
	s_waitcnt lgkmcnt(5)
	v_pk_fma_f32 v[52:53], v[60:61], v[110:111], v[52:53]
	v_lshlrev_b32_e32 v60, 16, v26
	v_and_b32_e32 v61, 0xffff0000, v26
	s_waitcnt lgkmcnt(3)
	v_pk_fma_f32 v[52:53], v[68:69], v[60:61], v[52:53]
	v_lshlrev_b32_e32 v68, 16, v19
	v_and_b32_e32 v69, 0xffff0000, v19
	v_pk_fma_f32 v[54:55], v[54:55], v[68:69], 0 op_sel_hi:[1,1,0]
	v_lshlrev_b32_e32 v68, 16, v23
	v_and_b32_e32 v69, 0xffff0000, v23
	v_lshlrev_b32_e32 v60, 16, v30
	v_and_b32_e32 v61, 0xffff0000, v30
	v_pk_fma_f32 v[54:55], v[62:63], v[68:69], v[54:55]
	v_lshlrev_b32_e32 v62, 16, v27
	v_and_b32_e32 v63, 0xffff0000, v27
	v_lshlrev_b32_e32 v68, 16, v20
	v_and_b32_e32 v69, 0xffff0000, v20
	s_waitcnt lgkmcnt(1)
	v_pk_fma_f32 v[52:53], v[76:77], v[60:61], v[52:53]
	v_pk_fma_f32 v[54:55], v[70:71], v[62:63], v[54:55]
	v_lshlrev_b32_e32 v62, 16, v31
	v_and_b32_e32 v63, 0xffff0000, v31
	v_pk_fma_f32 v[56:57], v[56:57], v[68:69], 0 op_sel_hi:[1,1,0]
	v_lshlrev_b32_e32 v68, 16, v24
	v_and_b32_e32 v69, 0xffff0000, v24
	v_mul_f32_e32 v60, 0xbfb8aa3b, v52
	v_mul_f32_e32 v61, 0xbfb8aa3b, v53
	v_pk_fma_f32 v[54:55], v[78:79], v[62:63], v[54:55]
	v_pk_fma_f32 v[56:57], v[64:65], v[68:69], v[56:57]
	v_lshlrev_b32_e32 v64, 16, v28
	v_and_b32_e32 v65, 0xffff0000, v28
	v_lshlrev_b32_e32 v68, 16, v21
	v_and_b32_e32 v69, 0xffff0000, v21
	v_exp_f32_e32 v60, v60
	v_exp_f32_e32 v61, v61
	v_mul_f32_e32 v62, 0xbfb8aa3b, v54
	v_mul_f32_e32 v63, 0xbfb8aa3b, v55
	v_pk_fma_f32 v[56:57], v[72:73], v[64:65], v[56:57]
	v_lshlrev_b32_e32 v64, 16, v32
	v_and_b32_e32 v65, 0xffff0000, v32
	v_pk_fma_f32 v[58:59], v[58:59], v[68:69], 0 op_sel_hi:[1,1,0]
	v_lshlrev_b32_e32 v68, 16, v25
	v_and_b32_e32 v69, 0xffff0000, v25
	v_exp_f32_e32 v62, v62
	v_exp_f32_e32 v63, v63
	s_waitcnt lgkmcnt(0)
; __device__ __forceinline__ float bflo(unsigned u) { return __uint_as_float(u << 16); }
; __device__ __forceinline__ float bfhi(unsigned u) { return __uint_as_float(u & 0xffff0000u); }
; DI float bflo(unsigned u) { return __uint_as_float(u << 16); }
; DI float bfhi(unsigned u) { return __uint_as_float(u & 0xffff0000u); }
; DI float dpp_xor1(float v) { return __int_as_float(__builtin_amdgcn_update_dpp(0, __float_as_int(v), 0xB1, 0xf, 0xf, false)); }
; DI float dpp_xor2(float v) { return __int_as_float(__builtin_amdgcn_update_dpp(0, __float_as_int(v), 0x4E, 0xf, 0xf, false)); }
; DI float dpp_half_mirror(float v) { return __int_as_float(__builtin_amdgcn_update_dpp(0, __float_as_int(v), 0x141, 0xf, 0xf, false)); }
; DI float sigmf(float v) { return __builtin_amdgcn_rcpf(1.0f + __expf(-v)); }
; DI float softplusf(float v) { return v > 20.f ? v : __logf(1.0f + __expf(v)); }
; #define PREP_BAR() do { asm volatile("s_waitcnt lgkmcnt(0)\n\ts_barrier" ::: "memory"); } while (0)
; DI void gdn_prep_unit(const Params& P, int h, int n, unsigned char* lds, int tid, u32x4 (&raw)[12], float& sbv, float& sav, int unext, bool cw_lds = false) {
;     ...
;             const float* wp = cw_lds ? (const float*)(lds + 86016) + (j * 3 + xx) * 64 + 8 * c8 : convw + j * 1536 + xx * 512 + h * 64 + 8 * c8;
;             const f32x4 w0 = *(const f32x4*)wp, w1 = *(const f32x4*)(wp + 4);
;             acc[0] += w0.x * bflo(rw.x); acc[1] += w0.y * bfhi(rw.x); acc[2] += w0.z * bflo(rw.y); acc[3] += w0.w * bfhi(rw.y);
;             acc[4] += w1.x * bflo(rw.z); acc[5] += w1.y * bfhi(rw.z); acc[6] += w1.z * bflo(rw.w); acc[7] += w1.w * bfhi(rw.w); }
; #pragma unroll
;         for (int e = 0; e < 8; ++e) y[xx][e] = acc[e] * sigmf(acc[e]);
;     }
;     const float sb_c = sbv, sa_c = sav;
;     float ssq = 0.f, ssk = 0.f;
; #pragma unroll
;     for (int e = 0; e < 8; ++e) { ssq += y[0][e] * y[0][e]; ssk += y[1][e] * y[1][e]; }
;     ssq += dpp_xor1(ssq); ssq += dpp_xor2(ssq); ssq += dpp_half_mirror(ssq);
;     ssk += dpp_xor1(ssk); ssk += dpp_xor2(ssk); ssk += dpp_half_mirror(ssk);
;     const float rq = rsqrtf(ssq + EPS) * 0.125f, rk = rsqrtf(ssk + EPS);
;     const float beta = sigmf(sb_c);
;     const float gt = -__expf(P.in[5][h]) * softplusf(sa_c + P.in[6][h]);
;     graw[t] = gt; bet[t] = beta;
;     PREP_BAR();
;     if (wave == 0) gcs[lane] = wave_incl_scan(graw[lane]);
	v_pk_fma_f32 v[56:57], v[80:81], v[64:65], v[56:57]
	v_pk_fma_f32 v[58:59], v[66:67], v[68:69], v[58:59]
	v_lshlrev_b32_e32 v66, 16, v29
	v_and_b32_e32 v67, 0xffff0000, v29
	v_mul_f32_e32 v64, 0xbfb8aa3b, v56
	v_mul_f32_e32 v65, 0xbfb8aa3b, v57
	v_pk_fma_f32 v[58:59], v[74:75], v[66:67], v[58:59]
	v_lshlrev_b32_e32 v66, 16, v33
	v_and_b32_e32 v67, 0xffff0000, v33
	v_exp_f32_e32 v64, v64
	v_exp_f32_e32 v65, v65
	v_pk_fma_f32 v[58:59], v[82:83], v[66:67], v[58:59]
	v_add_f32_e32 v60, 1.0, v60
	v_add_f32_e32 v61, 1.0, v61
	v_mul_f32_e32 v66, 0xbfb8aa3b, v58
	v_mul_f32_e32 v67, 0xbfb8aa3b, v59
	v_rcp_f32_e32 v60, v60
	v_rcp_f32_e32 v61, v61
	v_add_f32_e32 v62, 1.0, v62
	v_add_f32_e32 v63, 1.0, v63
	v_exp_f32_e32 v66, v66
	v_exp_f32_e32 v67, v67
	v_rcp_f32_e32 v62, v62
	v_rcp_f32_e32 v63, v63
	v_add_f32_e32 v64, 1.0, v64
	v_add_f32_e32 v65, 1.0, v65
	v_rcp_f32_e32 v64, v64
	v_rcp_f32_e32 v65, v65
	v_add_f32_e32 v66, 1.0, v66
	v_add_f32_e32 v67, 1.0, v67
	v_pk_mul_f32 v[114:115], v[52:53], v[60:61]
	v_rcp_f32_e32 v66, v66
	v_rcp_f32_e32 v67, v67
	v_pk_mul_f32 v[112:113], v[54:55], v[62:63]
	v_pk_mul_f32 v[118:119], v[100:101], v[100:101]
	v_pk_mul_f32 v[120:121], v[114:115], v[114:115]
	v_pk_mul_f32 v[222:223], v[102:103], v[102:103]
	v_pk_mul_f32 v[224:225], v[112:113], v[112:113]
	v_mov_b32_e32 v234, v120
	v_mov_b32_e32 v235, v118
	v_mov_b32_e32 v118, v121
	v_pk_mul_f32 v[110:111], v[56:57], v[64:65]
	v_pk_add_f32 v[118:119], v[234:235], v[118:119]
	v_mov_b32_e32 v120, v224
	v_mov_b32_e32 v121, v222
	v_pk_mul_f32 v[226:227], v[104:105], v[104:105]
	v_pk_mul_f32 v[228:229], v[110:111], v[110:111]
	v_pk_add_f32 v[118:119], v[120:121], v[118:119]
	v_mov_b32_e32 v222, v225
	v_pk_mul_f32 v[106:107], v[106:107], v[108:109]
	v_pk_mul_f32 v[108:109], v[58:59], v[66:67]
	v_pk_add_f32 v[118:119], v[222:223], v[118:119]
	v_mov_b32_e32 v120, v228
	v_mov_b32_e32 v121, v226
	v_pk_mul_f32 v[230:231], v[106:107], v[106:107]
	v_pk_mul_f32 v[232:233], v[108:109], v[108:109]
	v_pk_add_f32 v[118:119], v[120:121], v[118:119]
	v_mov_b32_e32 v226, v229
	v_pk_add_f32 v[118:119], v[226:227], v[118:119]
	v_mov_b32_e32 v120, v232
	v_mov_b32_e32 v121, v230
	v_pk_add_f32 v[118:119], v[120:121], v[118:119]
	v_mov_b32_e32 v230, v233
	v_pk_add_f32 v[118:119], v[230:231], v[118:119]
	v_mov_b32_e32 v121, v42
	v_mov_b32_e32 v120, v42
	v_add_f32_e32 v222, s101, v156
	v_mov_b32_dpp v121, v119 quad_perm:[1,0,3,2] row_mask:0xf bank_mask:0xf
	v_mov_b32_dpp v120, v118 quad_perm:[1,0,3,2] row_mask:0xf bank_mask:0xf
	v_pk_add_f32 v[118:119], v[118:119], v[120:121]
	v_mov_b32_e32 v121, v42
	v_mov_b32_e32 v120, v42
	ds_read_b128 v[80:83], v116 offset:512
	ds_read_b128 v[64:67], v116 offset:528
	ds_read_b128 v[76:79], v116 offset:1280
	ds_read_b128 v[60:63], v116 offset:1296
	ds_read_b128 v[72:75], v116 offset:2048
	ds_read_b128 v[56:59], v116 offset:2064
	ds_read_b128 v[68:71], v116 offset:2816
	ds_read_b128 v[52:55], v116 offset:2832
	v_mov_b32_dpp v121, v119 quad_perm:[2,3,0,1] row_mask:0xf bank_mask:0xf
	v_mov_b32_dpp v120, v118 quad_perm:[2,3,0,1] row_mask:0xf bank_mask:0xf
	v_pk_add_f32 v[118:119], v[118:119], v[120:121]
	v_mul_f32_e32 v120, 0x3fb8aa3b, v222
	v_exp_f32_e32 v223, v120
	v_mul_f32_e32 v116, 0xbfb8aa3b, v43
	v_exp_f32_e32 v116, v116
	s_mov_b32 s0, 0x3f317217
	v_add_f32_e32 v223, 1.0, v223
	v_cmp_gt_f32_e32 vcc, s58, v223
	v_add_f32_e32 v116, 1.0, v116
	v_rcp_f32_e32 v116, v116
	v_cndmask_b32_e64 v224, 0, 32, vcc
	v_ldexp_f32 v223, v223, v224
	v_log_f32_e32 v223, v223
	v_mov_b32_e32 v224, s100
	v_mul_f32_e32 v224, 0x3fb8aa3b, v224
	v_exp_f32_e32 v224, v224
	v_mov_b32_e32 v121, 0
	v_mul_f32_e32 v225, 0x3f317217, v223
	v_fma_f32 v225, v223, s0, -v225
	v_fmac_f32_e32 v225, 0x3377d1cf, v223
	s_mov_b32 s0, 0x7f800000
	v_fmac_f32_e32 v225, 0x3f317217, v223
	v_cmp_lt_f32_e64 s[0:1], |v223|, s0
	v_mov_b32_e32 v120, 0
	v_mov_b32_dpp v121, v119 row_half_mirror row_mask:0xf bank_mask:0xf
	v_cndmask_b32_e64 v223, v223, v225, s[0:1]
	v_cndmask_b32_e32 v225, 0, v217, vcc
	s_mov_b32 s0, 0x41a00000
	v_sub_f32_e32 v223, v223, v225
	v_cmp_lt_f32_e32 vcc, s0, v222
	v_mov_b32_dpp v120, v118 row_half_mirror row_mask:0xf bank_mask:0xf
	s_nop 0
	v_cndmask_b32_e32 v222, v223, v222, vcc
	v_mul_f32_e64 v222, v222, -v224
	ds_write_b32 v132, v222
	ds_write_b32 v133, v116
	s_waitcnt lgkmcnt(0)
	s_barrier
	s_and_saveexec_b64 s[0:1], s[8:9]
	s_cbranch_execz .LBB0_494
	ds_read_b32 v222, v134
	v_mov_b32_e32 v223, v42
	s_waitcnt lgkmcnt(0)
	v_add_f32_dpp v222, v222, v222 row_shr:1 row_mask:0xf bank_mask:0xf bound_ctrl:1
	s_nop 1
	v_add_f32_dpp v222, v222, v222 row_shr:2 row_mask:0xf bank_mask:0xf bound_ctrl:1
	s_nop 1
	v_add_f32_dpp v222, v222, v222 row_shr:4 row_mask:0xf bank_mask:0xf bound_ctrl:1
	s_nop 1
	v_add_f32_dpp v222, v222, v222 row_shr:8 row_mask:0xf bank_mask:0xf bound_ctrl:1
	s_nop 1
	v_mov_b32_dpp v223, v222 row_bcast:15 row_mask:0xa bank_mask:0xf
	v_add_f32_e32 v222, v222, v223
	v_mov_b32_e32 v223, v42
	s_nop 1
	v_mov_b32_dpp v223, v222 row_bcast:31 row_mask:0xc bank_mask:0xf
	v_add_f32_e32 v222, v222, v223
	ds_write_b32 v135, v222
